# cand17 + P2 mixing-matrix set-up: 8 row loads issued together with counted waits
# baseline (speedup 1.0000x reference)
.LBB0_571:
	s_or_b64 exec, exec, s[26:27]
	v_and_b32_e32 v139, 31, v203
	s_and_b32 s49, s48, 15
	v_and_b32_e32 v206, 15, v203
	s_cmp_lg_u32 s49, s28
	v_lshlrev_b32_e32 v190, 3, v139
	v_ashrrev_i32_e32 v140, 5, v203
	s_cbranch_scc0 .LBB0_573
	v_lshlrev_b32_e32 v98, 2, v203
	v_and_b32_e32 v141, 0x7c, v98
	v_ashrrev_i32_e32 v192, 5, v203
	s_lshl_b32 s22, s49, 7
	v_lshlrev_b32_e32 v98, 2, v141
	v_mov_b32_e32 v99, v191
	v_ashrrev_i32_e32 v193, 31, v192
	v_lshl_add_u64 v[102:103], s[8:9], 0, v[98:99]
	v_lshl_add_u64 v[98:99], v[192:193], 0, s[22:23]
	v_lshlrev_b64 v[98:99], 9, v[98:99]
	v_lshl_add_u64 v[98:99], v[102:103], 0, v[98:99]
	s_waitcnt lgkmcnt(0)
	s_mov_b64 s[98:99], 0x2000
	v_lshl_add_u64 v[174:175], v[98:99], 0, s[98:99]
	global_load_dwordx4 v[98:101], v[98:99], off
	global_load_dwordx4 v[146:149], v[174:175], off
	v_lshl_add_u64 v[174:175], v[174:175], 0, s[98:99]
	global_load_dwordx4 v[150:153], v[174:175], off
	v_lshl_add_u64 v[174:175], v[174:175], 0, s[98:99]
	global_load_dwordx4 v[154:157], v[174:175], off
	v_lshl_add_u64 v[174:175], v[174:175], 0, s[98:99]
	global_load_dwordx4 v[158:161], v[174:175], off
	v_lshl_add_u64 v[174:175], v[174:175], 0, s[98:99]
	global_load_dwordx4 v[162:165], v[174:175], off
	v_lshl_add_u64 v[174:175], v[174:175], 0, s[98:99]
	global_load_dwordx4 v[166:169], v[174:175], off
	v_lshl_add_u64 v[174:175], v[174:175], 0, s[98:99]
	global_load_dwordx4 v[170:173], v[174:175], off
	v_add_u32_e32 v104, 0x200, v203
	v_ashrrev_i32_e32 v104, 5, v104
	v_cmp_le_i32_e32 vcc, v141, v192
	v_or_b32_e32 v144, 2, v141
	v_ashrrev_i32_e32 v105, 31, v104
	v_or_b32_e32 v145, 3, v141
	v_lshl_add_u64 v[106:107], v[104:105], 0, s[22:23]
	v_lshlrev_b64 v[106:107], 9, v[106:107]
	v_lshl_add_u64 v[106:107], v[102:103], 0, v[106:107]
	v_add_u32_e32 v105, 0x400, v203
	v_lshl_add_u32 v130, v141, 1, s45
	v_mad_u64_u32 v[110:111], s[0:1], v192, s46, v[130:131]
	s_lshl_b32 s26, s49, 8
	s_lshl_b32 s27, s49, 10
	s_waitcnt vmcnt(7)
	v_cndmask_b32_e32 v98, 0, v98, vcc
	v_cmp_lt_i32_e32 vcc, v141, v192
	s_nop 1
	v_cndmask_b32_e32 v99, 0, v99, vcc
	v_cmp_le_i32_e32 vcc, v144, v192
	v_cvt_pk_bf16_f32 v108, v98, v99
	s_nop 1
	v_cndmask_b32_e32 v100, 0, v100, vcc
	v_cmp_le_i32_e32 vcc, v145, v192
	s_nop 1
	v_cndmask_b32_e32 v101, 0, v101, vcc
	v_cvt_pk_bf16_f32 v109, v100, v101
	s_waitcnt vmcnt(6)
	v_mov_b64_e32 v[98:99], v[146:147]
	v_mov_b64_e32 v[100:101], v[148:149]
	v_ashrrev_i32_e32 v106, 5, v105
	v_cmp_le_i32_e32 vcc, v141, v104
	v_ashrrev_i32_e32 v107, 31, v106
	v_lshl_add_u64 v[112:113], v[106:107], 0, s[22:23]
	v_lshlrev_b64 v[112:113], 9, v[112:113]
	v_lshl_add_u64 v[112:113], v[102:103], 0, v[112:113]
	ds_write_b64 v110, v[108:109]
	v_add_u32_e32 v105, 0x600, v203
	v_ashrrev_i32_e32 v110, 5, v105
	v_ashrrev_i32_e32 v111, 31, v110
	v_add_u32_e32 v107, 0x800, v203
	s_nop 1
	v_cndmask_b32_e32 v98, 0, v98, vcc
	v_cmp_lt_i32_e32 vcc, v141, v104
	s_nop 1
	v_cndmask_b32_e32 v99, 0, v99, vcc
	v_cmp_le_i32_e32 vcc, v144, v104
	v_cvt_pk_bf16_f32 v108, v98, v99
	s_nop 1
	v_cndmask_b32_e32 v100, 0, v100, vcc
	v_cmp_le_i32_e32 vcc, v145, v104
	v_mad_u64_u32 v[104:105], s[0:1], v104, s46, v[130:131]
	s_nop 0
	v_cndmask_b32_e32 v101, 0, v101, vcc
	v_cvt_pk_bf16_f32 v109, v100, v101
	s_waitcnt vmcnt(5)
	v_mov_b64_e32 v[98:99], v[150:151]
	v_mov_b64_e32 v[100:101], v[152:153]
	v_cmp_le_i32_e32 vcc, v141, v106
	v_lshl_add_u64 v[112:113], v[110:111], 0, s[22:23]
	v_lshlrev_b64 v[112:113], 9, v[112:113]
	v_lshl_add_u64 v[112:113], v[102:103], 0, v[112:113]
	ds_write_b64 v104, v[108:109]
	v_ashrrev_i32_e32 v108, 5, v107
	v_ashrrev_i32_e32 v109, 31, v108
	s_nop 1
	v_cndmask_b32_e32 v98, 0, v98, vcc
	v_cmp_lt_i32_e32 vcc, v141, v106
	s_nop 1
	v_cndmask_b32_e32 v99, 0, v99, vcc
	v_cmp_le_i32_e32 vcc, v144, v106
	v_cvt_pk_bf16_f32 v104, v98, v99
	s_nop 1
	v_cndmask_b32_e32 v100, 0, v100, vcc
	v_cmp_le_i32_e32 vcc, v145, v106
	v_mad_u64_u32 v[106:107], s[0:1], v106, s46, v[130:131]
	s_nop 0
	v_cndmask_b32_e32 v101, 0, v101, vcc
	v_cvt_pk_bf16_f32 v105, v100, v101
	s_waitcnt vmcnt(4)
	v_mov_b64_e32 v[98:99], v[154:155]
	v_mov_b64_e32 v[100:101], v[156:157]
	v_cmp_le_i32_e32 vcc, v141, v110
	v_lshl_add_u64 v[112:113], v[108:109], 0, s[22:23]
	v_lshlrev_b64 v[112:113], 9, v[112:113]
	v_lshl_add_u64 v[112:113], v[102:103], 0, v[112:113]
	ds_write_b64 v106, v[104:105]
	v_add_u32_e32 v106, 0xa00, v203
	v_ashrrev_i32_e32 v106, 5, v106
	v_ashrrev_i32_e32 v107, 31, v106
	s_nop 1
	v_cndmask_b32_e32 v98, 0, v98, vcc
	v_cmp_lt_i32_e32 vcc, v141, v110
	s_nop 1
	v_cndmask_b32_e32 v99, 0, v99, vcc
	v_cmp_le_i32_e32 vcc, v144, v110
	v_cvt_pk_bf16_f32 v104, v98, v99
	s_nop 1
	v_cndmask_b32_e32 v100, 0, v100, vcc
	v_cmp_le_i32_e32 vcc, v145, v110
	v_mad_u64_u32 v[110:111], s[0:1], v110, s46, v[130:131]
	s_nop 0
	v_cndmask_b32_e32 v101, 0, v101, vcc
	v_cvt_pk_bf16_f32 v105, v100, v101
	s_waitcnt vmcnt(3)
	v_mov_b64_e32 v[98:99], v[158:159]
	v_mov_b64_e32 v[100:101], v[160:161]
	v_cmp_le_i32_e32 vcc, v141, v108
	v_lshl_add_u64 v[112:113], v[106:107], 0, s[22:23]
	v_lshlrev_b64 v[112:113], 9, v[112:113]
	v_lshl_add_u64 v[112:113], v[102:103], 0, v[112:113]
	ds_write_b64 v110, v[104:105]
	v_add_u32_e32 v107, 0xc00, v203
	v_ashrrev_i32_e32 v110, 5, v107
	v_ashrrev_i32_e32 v111, 31, v110
	v_add_u32_e32 v107, 0xe00, v203
	v_ashrrev_i32_e32 v142, 5, v107
	v_ashrrev_i32_e32 v143, 31, v142
	s_nop 1
	v_cndmask_b32_e32 v98, 0, v98, vcc
	v_cmp_lt_i32_e32 vcc, v141, v108
	s_nop 1
	v_cndmask_b32_e32 v99, 0, v99, vcc
	v_cmp_le_i32_e32 vcc, v144, v108
	v_cvt_pk_bf16_f32 v104, v98, v99
	s_nop 1
	v_cndmask_b32_e32 v100, 0, v100, vcc
	v_cmp_le_i32_e32 vcc, v145, v108
	v_mad_u64_u32 v[108:109], s[0:1], v108, s46, v[130:131]
	s_nop 0
	v_cndmask_b32_e32 v101, 0, v101, vcc
	v_cvt_pk_bf16_f32 v105, v100, v101
	s_waitcnt vmcnt(2)
	v_mov_b64_e32 v[98:99], v[162:163]
	v_mov_b64_e32 v[100:101], v[164:165]
	v_cmp_le_i32_e32 vcc, v141, v106
	v_lshl_add_u64 v[112:113], v[110:111], 0, s[22:23]
	v_lshlrev_b64 v[112:113], 9, v[112:113]
	v_lshl_add_u64 v[112:113], v[102:103], 0, v[112:113]
	ds_write_b64 v108, v[104:105]
	v_lshl_add_u64 v[108:109], v[142:143], 0, s[22:23]
	v_lshlrev_b64 v[108:109], 9, v[108:109]
	v_lshl_add_u64 v[102:103], v[102:103], 0, v[108:109]
	s_nop 1
	v_cndmask_b32_e32 v98, 0, v98, vcc
	v_cmp_lt_i32_e32 vcc, v141, v106
	s_nop 1
	v_cndmask_b32_e32 v99, 0, v99, vcc
	v_cmp_le_i32_e32 vcc, v144, v106
	v_cvt_pk_bf16_f32 v104, v98, v99
	s_nop 1
	v_cndmask_b32_e32 v100, 0, v100, vcc
	v_cmp_le_i32_e32 vcc, v145, v106
	v_mad_u64_u32 v[106:107], s[0:1], v106, s46, v[130:131]
	s_nop 0
	v_cndmask_b32_e32 v101, 0, v101, vcc
	v_cvt_pk_bf16_f32 v105, v100, v101
	s_waitcnt vmcnt(1)
	v_mov_b64_e32 v[98:99], v[166:167]
	v_mov_b64_e32 v[100:101], v[168:169]
	v_cmp_le_i32_e32 vcc, v141, v110
	ds_write_b64 v106, v[104:105]
	s_add_u32 s0, s4, s27
	s_addc_u32 s1, s5, 0
	v_lshlrev_b32_e32 v106, 5, v139
	s_nop 1
	v_cndmask_b32_e32 v98, 0, v98, vcc
	v_cmp_lt_i32_e32 vcc, v141, v110
	s_nop 1
	v_cndmask_b32_e32 v99, 0, v99, vcc
	v_cmp_le_i32_e32 vcc, v144, v110
	v_cvt_pk_bf16_f32 v104, v98, v99
	s_nop 1
	v_cndmask_b32_e32 v100, 0, v100, vcc
	v_cmp_le_i32_e32 vcc, v145, v110
	s_nop 1
	v_cndmask_b32_e32 v101, 0, v101, vcc
	v_cvt_pk_bf16_f32 v105, v100, v101
	s_waitcnt vmcnt(0)
	v_mov_b64_e32 v[98:99], v[170:171]
	v_mov_b64_e32 v[100:101], v[172:173]
	v_cmp_le_i32_e32 vcc, v141, v142
	v_or_b32_e32 v102, s22, v206
	v_lshlrev_b32_e32 v143, 2, v102
	v_mad_u64_u32 v[102:103], s[30:31], v110, s46, v[130:131]
	s_add_u32 s30, s6, s27
	s_addc_u32 s31, s7, 0
	ds_write_b64 v102, v[104:105]
	s_mov_b32 s27, s23
	s_nop 1
	v_cndmask_b32_e32 v98, 0, v98, vcc
	v_cmp_lt_i32_e32 vcc, v141, v142
	s_nop 1
	v_cndmask_b32_e32 v99, 0, v99, vcc
	v_cmp_le_i32_e32 vcc, v144, v142
	v_cvt_pk_bf16_f32 v144, v98, v99
	s_nop 1
	v_cndmask_b32_e32 v100, 0, v100, vcc
	v_cmp_le_i32_e32 vcc, v145, v142
	s_nop 1
	v_cndmask_b32_e32 v101, 0, v101, vcc
	v_cvt_pk_bf16_f32 v145, v100, v101
	global_load_dwordx4 v[102:105], v106, s[0:1] offset:16
	global_load_dwordx4 v[110:113], v106, s[0:1]
	global_load_dwordx4 v[98:101], v106, s[30:31] offset:16
	s_nop 0
	global_load_dwordx4 v[106:109], v106, s[30:31]
	s_nop 0
	global_load_dword v193, v143, s[10:11]
	global_load_dword v196, v143, s[10:11] offset:64
	global_load_dword v197, v143, s[10:11] offset:128
	global_load_dword v198, v143, s[10:11] offset:192
	global_load_dword v199, v143, s[10:11] offset:256
	global_load_dword v200, v143, s[10:11] offset:320
	global_load_dword v201, v143, s[10:11] offset:384
	global_load_dword v202, v143, s[10:11] offset:448
	v_mad_u64_u32 v[142:143], s[0:1], v142, s46, v[130:131]
	ds_write_b64 v142, v[144:145]
	s_cbranch_execz .LBB0_574
	s_branch .LBB0_575
